# as previous + residual-epilogue (EpiRes) loads software-pipelined two row groups ahead through a 3-slot register ring with counted vmcnt
# baseline (speedup 1.0000x reference)
.LBB0_1018:
	v_lshl_add_u32 v142, s78, 8, v144
	v_lshl_or_b32 v140, s79, 8, v146
	v_ashrrev_i32_e32 v143, 31, v142
	v_ashrrev_i32_e32 v141, 31, v140
	v_lshlrev_b64 v[148:149], 10, v[142:143]
	v_lshl_add_u64 v[156:157], v[148:149], 0, v[140:141]
	v_lshlrev_b64 v[158:159], 2, v[156:157]
	v_lshl_add_u64 v[160:161], s[6:7], 0, v[158:159]
	v_mov_b32_e32 v240, 0x10000
	v_mov_b32_e32 v241, 0
	v_mov_b32_e32 v242, 0x50000
	v_mov_b32_e32 v243, 0
	v_mov_b64_e32 v[236:237], v[160:161]
	global_load_dwordx4 v[188:191], v[236:237], off offset:16
	global_load_dwordx4 v[192:195], v[236:237], off
	global_load_dwordx4 v[196:199], v[236:237], off offset:528
	global_load_dwordx4 v[200:203], v[236:237], off offset:512
	v_lshl_add_u64 v[238:239], v[236:237], 0, v[240:241]
	global_load_dwordx4 v[204:207], v[238:239], off offset:16
	global_load_dwordx4 v[208:211], v[238:239], off
	global_load_dwordx4 v[212:215], v[238:239], off offset:528
	global_load_dwordx4 v[216:219], v[238:239], off offset:512
	v_lshl_add_u64 v[186:187], v[238:239], 0, v[240:241]
	global_load_dwordx4 v[220:223], v[186:187], off offset:16
	global_load_dwordx4 v[224:227], v[186:187], off
	global_load_dwordx4 v[228:231], v[186:187], off offset:528
	global_load_dwordx4 v[232:235], v[186:187], off offset:512
	s_nop 0
	v_lshlrev_b64 v[156:157], 1, v[156:157]
	v_lshl_add_u64 v[158:159], s[48:49], 0, v[158:159]
	s_waitcnt vmcnt(8)
	v_pk_fma_f32 v[124:125], s[20:21], v[124:125], v[190:191]
	v_pk_fma_f32 v[128:129], s[20:21], v[128:129], v[194:195]
	v_pk_fma_f32 v[126:127], s[4:5], v[126:127], v[192:193]
	v_pk_fma_f32 v[122:123], s[4:5], v[122:123], v[188:189]
	v_cvt_pk_bf16_f32 v148, v126, v127
	v_cvt_pk_bf16_f32 v149, v128, v129
	v_cvt_pk_bf16_f32 v150, v122, v123
	v_cvt_pk_bf16_f32 v151, v124, v125
	v_lshl_add_u64 v[152:153], s[40:41], 0, v[156:157]
	global_store_dwordx4 v[158:159], v[126:129], off
	global_store_dwordx4 v[158:159], v[122:125], off offset:16
	global_store_dwordx4 v[152:153], v[148:151], off
	s_nop 0
	s_nop 0
	s_nop 0
	v_mul_f32_e32 v125, v125, v125
	v_mul_f32_e32 v123, v123, v123
	v_fmac_f32_e32 v125, v124, v124
	v_fmac_f32_e32 v123, v122, v122
	v_mul_f32_e32 v122, v127, v127
	v_mul_f32_e32 v124, v129, v129
	v_fmac_f32_e32 v122, v126, v126
	v_fmac_f32_e32 v124, v128, v128
	v_add_f32_e32 v122, v122, v124
	v_add_f32_e32 v122, v123, v122
	v_add_f32_e32 v122, v125, v122
	v_or_b32_e32 v156, 0x100, v156
	s_nop 0
	v_pk_fma_f32 v[116:117], s[20:21], v[116:117], v[198:199]
	s_nop 0
	v_pk_fma_f32 v[120:121], s[20:21], v[120:121], v[202:203]
	v_pk_fma_f32 v[118:119], s[4:5], v[118:119], v[200:201]
	v_pk_fma_f32 v[114:115], s[4:5], v[114:115], v[196:197]
	global_store_dwordx4 v[158:159], v[118:121], off offset:512
	global_store_dwordx4 v[158:159], v[114:117], off offset:528
	v_cvt_pk_bf16_f32 v150, v114, v115
	v_cvt_pk_bf16_f32 v151, v116, v117
	v_mul_f32_e32 v117, v117, v117
	v_mul_f32_e32 v115, v115, v115
	v_fmac_f32_e32 v117, v116, v116
	v_fmac_f32_e32 v115, v114, v114
	v_mul_f32_e32 v114, v119, v119
	v_mul_f32_e32 v116, v121, v121
	v_fmac_f32_e32 v114, v118, v118
	v_fmac_f32_e32 v116, v120, v120
	v_add_f32_e32 v114, v114, v116
	v_add_f32_e32 v114, v115, v114
	v_and_b32_e32 v116, 64, v183
	v_add_f32_e32 v114, v117, v114
	v_xor_b32_e32 v115, 16, v183
	v_add_u32_e32 v117, 64, v116
	v_cmp_lt_i32_e32 vcc, v115, v117
	v_add_f32_e32 v114, v122, v114
	v_cvt_pk_bf16_f32 v148, v118, v119
	v_cndmask_b32_e32 v115, v183, v115, vcc
	v_lshlrev_b32_e32 v116, 2, v115
	ds_bpermute_b32 v115, v116, v114
	v_cvt_pk_bf16_f32 v149, v120, v121
	v_lshl_add_u64 v[152:153], s[40:41], 0, v[156:157]
	global_store_dwordx4 v[152:153], v[148:151], off
	s_waitcnt lgkmcnt(0)
	v_add_f32_e32 v114, v114, v115
	v_xor_b32_e32 v115, 32, v183
	v_cmp_lt_i32_e32 vcc, v115, v117
	s_nop 1
	v_cndmask_b32_e32 v115, v183, v115, vcc
	v_lshlrev_b32_e32 v117, 2, v115
	ds_bpermute_b32 v115, v117, v114
	s_and_saveexec_b64 s[60:61], s[44:45]
	s_cbranch_execz .LBB0_1020
	v_lshl_add_u64 v[118:119], v[142:143], 2, s[14:15]
	s_waitcnt lgkmcnt(0)
	v_add_f32_e32 v114, v114, v115
	global_atomic_add_f32 v[118:119], v114, off
.LBB0_1020:
	s_or_b64 exec, exec, s[60:61]
	v_or_b32_e32 v114, 16, v142
	s_waitcnt lgkmcnt(0)
	v_ashrrev_i32_e32 v115, 31, v114
	v_lshlrev_b64 v[118:119], 10, v[114:115]
	v_lshl_add_u64 v[126:127], v[118:119], 0, v[140:141]
	v_lshlrev_b64 v[128:129], 2, v[126:127]
	v_lshl_add_u64 v[148:149], s[6:7], 0, v[128:129]
	v_lshl_add_u64 v[236:237], v[186:187], 0, v[240:241]
	global_load_dwordx4 v[188:191], v[236:237], off offset:16
	global_load_dwordx4 v[192:195], v[236:237], off
	global_load_dwordx4 v[196:199], v[236:237], off offset:528
	global_load_dwordx4 v[200:203], v[236:237], off offset:512
	s_nop 0
	v_lshlrev_b64 v[126:127], 1, v[126:127]
	v_lshl_add_u64 v[128:129], s[48:49], 0, v[128:129]
	s_waitcnt vmcnt(14)
	v_pk_fma_f32 v[108:109], s[20:21], v[108:109], v[206:207]
	s_nop 0
	v_pk_fma_f32 v[112:113], s[20:21], v[112:113], v[210:211]
	v_pk_fma_f32 v[110:111], s[4:5], v[110:111], v[208:209]
	v_pk_fma_f32 v[106:107], s[4:5], v[106:107], v[204:205]
	v_cvt_pk_bf16_f32 v118, v110, v111
	v_cvt_pk_bf16_f32 v119, v112, v113
	v_cvt_pk_bf16_f32 v120, v106, v107
	v_cvt_pk_bf16_f32 v121, v108, v109
	v_lshl_add_u64 v[122:123], s[40:41], 0, v[126:127]
	global_store_dwordx4 v[128:129], v[110:113], off
	global_store_dwordx4 v[128:129], v[106:109], off offset:16
	global_store_dwordx4 v[122:123], v[118:121], off
	s_nop 0
	s_nop 0
	s_nop 0
	v_mul_f32_e32 v109, v109, v109
	v_mul_f32_e32 v107, v107, v107
	v_fmac_f32_e32 v109, v108, v108
	v_fmac_f32_e32 v107, v106, v106
	v_mul_f32_e32 v106, v111, v111
	v_mul_f32_e32 v108, v113, v113
	v_fmac_f32_e32 v106, v110, v110
	v_fmac_f32_e32 v108, v112, v112
	v_add_f32_e32 v106, v106, v108
	v_add_f32_e32 v106, v107, v106
	v_add_f32_e32 v106, v109, v106
	v_or_b32_e32 v126, 0x100, v126
	s_nop 0
	v_pk_fma_f32 v[100:101], s[20:21], v[100:101], v[214:215]
	s_nop 0
	v_pk_fma_f32 v[104:105], s[20:21], v[104:105], v[218:219]
	v_pk_fma_f32 v[102:103], s[4:5], v[102:103], v[216:217]
	v_pk_fma_f32 v[98:99], s[4:5], v[98:99], v[212:213]
	global_store_dwordx4 v[128:129], v[102:105], off offset:512
	global_store_dwordx4 v[128:129], v[98:101], off offset:528
	v_cvt_pk_bf16_f32 v120, v98, v99
	v_cvt_pk_bf16_f32 v121, v100, v101
	v_mul_f32_e32 v101, v101, v101
	v_mul_f32_e32 v99, v99, v99
	v_fmac_f32_e32 v101, v100, v100
	v_fmac_f32_e32 v99, v98, v98
	v_mul_f32_e32 v98, v103, v103
	v_mul_f32_e32 v100, v105, v105
	v_fmac_f32_e32 v98, v102, v102
	v_fmac_f32_e32 v100, v104, v104
	v_add_f32_e32 v98, v98, v100
	v_add_f32_e32 v98, v99, v98
	v_add_f32_e32 v98, v101, v98
	v_add_f32_e32 v98, v106, v98
	ds_bpermute_b32 v99, v116, v98
	v_cvt_pk_bf16_f32 v118, v102, v103
	v_cvt_pk_bf16_f32 v119, v104, v105
	v_lshl_add_u64 v[122:123], s[40:41], 0, v[126:127]
	global_store_dwordx4 v[122:123], v[118:121], off
	s_waitcnt lgkmcnt(0)
	v_add_f32_e32 v98, v98, v99
	ds_bpermute_b32 v99, v117, v98
	s_and_saveexec_b64 s[60:61], s[44:45]
	s_cbranch_execz .LBB0_1022
	v_lshl_add_u64 v[100:101], v[114:115], 2, s[14:15]
	s_waitcnt lgkmcnt(0)
	v_add_f32_e32 v98, v98, v99
	global_atomic_add_f32 v[100:101], v98, off
.LBB0_1022:
	s_or_b64 exec, exec, s[60:61]
	v_or_b32_e32 v98, 32, v142
	s_waitcnt lgkmcnt(0)
	v_ashrrev_i32_e32 v99, 31, v98
	v_lshlrev_b64 v[100:101], 10, v[98:99]
	v_lshl_add_u64 v[108:109], v[100:101], 0, v[140:141]
	v_lshlrev_b64 v[110:111], 2, v[108:109]
	v_lshl_add_u64 v[112:113], s[6:7], 0, v[110:111]
	v_lshl_add_u64 v[238:239], v[236:237], 0, v[242:243]
	global_load_dwordx4 v[204:207], v[238:239], off offset:16
	global_load_dwordx4 v[208:211], v[238:239], off
	global_load_dwordx4 v[212:215], v[238:239], off offset:528
	global_load_dwordx4 v[216:219], v[238:239], off offset:512
	s_nop 0
	v_lshlrev_b64 v[108:109], 1, v[108:109]
	v_lshl_add_u64 v[110:111], s[48:49], 0, v[110:111]
	s_waitcnt vmcnt(20)
	v_pk_fma_f32 v[92:93], s[20:21], v[92:93], v[222:223]
	s_nop 0
	v_pk_fma_f32 v[96:97], s[20:21], v[96:97], v[226:227]
	v_pk_fma_f32 v[94:95], s[4:5], v[94:95], v[224:225]
	v_pk_fma_f32 v[90:91], s[4:5], v[90:91], v[220:221]
	v_cvt_pk_bf16_f32 v100, v94, v95
	v_cvt_pk_bf16_f32 v101, v96, v97
	v_cvt_pk_bf16_f32 v102, v90, v91
	v_cvt_pk_bf16_f32 v103, v92, v93
	v_lshl_add_u64 v[104:105], s[40:41], 0, v[108:109]
	global_store_dwordx4 v[110:111], v[94:97], off
	global_store_dwordx4 v[110:111], v[90:93], off offset:16
	global_store_dwordx4 v[104:105], v[100:103], off
	s_nop 0
	s_nop 0
	s_nop 0
	v_mul_f32_e32 v93, v93, v93
	v_mul_f32_e32 v91, v91, v91
	v_fmac_f32_e32 v93, v92, v92
	v_fmac_f32_e32 v91, v90, v90
	v_mul_f32_e32 v90, v95, v95
	v_mul_f32_e32 v92, v97, v97
	v_fmac_f32_e32 v90, v94, v94
	v_fmac_f32_e32 v92, v96, v96
	v_add_f32_e32 v90, v90, v92
	v_add_f32_e32 v90, v91, v90
	v_add_f32_e32 v90, v93, v90
	v_or_b32_e32 v108, 0x100, v108
	s_nop 0
	v_pk_fma_f32 v[84:85], s[20:21], v[84:85], v[230:231]
	s_nop 0
	v_pk_fma_f32 v[88:89], s[20:21], v[88:89], v[234:235]
	v_pk_fma_f32 v[86:87], s[4:5], v[86:87], v[232:233]
	v_pk_fma_f32 v[82:83], s[4:5], v[82:83], v[228:229]
	global_store_dwordx4 v[110:111], v[86:89], off offset:512
	global_store_dwordx4 v[110:111], v[82:85], off offset:528
	v_cvt_pk_bf16_f32 v102, v82, v83
	v_cvt_pk_bf16_f32 v103, v84, v85
	v_mul_f32_e32 v85, v85, v85
	v_mul_f32_e32 v83, v83, v83
	v_fmac_f32_e32 v85, v84, v84
	v_fmac_f32_e32 v83, v82, v82
	v_mul_f32_e32 v82, v87, v87
	v_mul_f32_e32 v84, v89, v89
	v_fmac_f32_e32 v82, v86, v86
	v_fmac_f32_e32 v84, v88, v88
	v_add_f32_e32 v82, v82, v84
	v_add_f32_e32 v82, v83, v82
	v_add_f32_e32 v82, v85, v82
	v_add_f32_e32 v82, v90, v82
	ds_bpermute_b32 v83, v116, v82
	v_cvt_pk_bf16_f32 v100, v86, v87
	v_cvt_pk_bf16_f32 v101, v88, v89
	v_lshl_add_u64 v[104:105], s[40:41], 0, v[108:109]
	global_store_dwordx4 v[104:105], v[100:103], off
	s_waitcnt lgkmcnt(0)
	v_add_f32_e32 v82, v82, v83
	ds_bpermute_b32 v83, v117, v82
	s_and_saveexec_b64 s[60:61], s[44:45]
	s_mov_b32 s84, 0xbf3a00e3
	s_cbranch_execz .LBB0_1024
	v_lshl_add_u64 v[84:85], v[98:99], 2, s[14:15]
	s_waitcnt lgkmcnt(0)
	v_add_f32_e32 v82, v82, v83
	global_atomic_add_f32 v[84:85], v82, off
.LBB0_1024:
	s_or_b64 exec, exec, s[60:61]
	v_or_b32_e32 v82, 48, v142
	s_waitcnt lgkmcnt(0)
	v_ashrrev_i32_e32 v83, 31, v82
	v_lshlrev_b64 v[84:85], 10, v[82:83]
	v_lshl_add_u64 v[92:93], v[84:85], 0, v[140:141]
	v_lshlrev_b64 v[94:95], 2, v[92:93]
	v_lshl_add_u64 v[96:97], s[6:7], 0, v[94:95]
	v_lshl_add_u64 v[186:187], v[238:239], 0, v[240:241]
	global_load_dwordx4 v[220:223], v[186:187], off offset:16
	global_load_dwordx4 v[224:227], v[186:187], off
	global_load_dwordx4 v[228:231], v[186:187], off offset:528
	global_load_dwordx4 v[232:235], v[186:187], off offset:512
	s_nop 0
	v_lshlrev_b64 v[92:93], 1, v[92:93]
	v_lshl_add_u64 v[94:95], s[48:49], 0, v[94:95]
	s_waitcnt vmcnt(20)
	v_pk_fma_f32 v[74:75], s[20:21], v[74:75], v[190:191]
	s_nop 0
	v_pk_fma_f32 v[78:79], s[20:21], v[78:79], v[194:195]
	v_pk_fma_f32 v[76:77], s[4:5], v[76:77], v[192:193]
	v_pk_fma_f32 v[72:73], s[4:5], v[72:73], v[188:189]
	v_cvt_pk_bf16_f32 v84, v76, v77
	v_cvt_pk_bf16_f32 v85, v78, v79
	v_cvt_pk_bf16_f32 v86, v72, v73
	v_cvt_pk_bf16_f32 v87, v74, v75
	v_lshl_add_u64 v[88:89], s[40:41], 0, v[92:93]
	global_store_dwordx4 v[94:95], v[76:79], off
	global_store_dwordx4 v[94:95], v[72:75], off offset:16
	global_store_dwordx4 v[88:89], v[84:87], off
	s_nop 0
	s_nop 0
	s_nop 0
	v_mul_f32_e32 v75, v75, v75
	v_mul_f32_e32 v73, v73, v73
	v_fmac_f32_e32 v75, v74, v74
	v_fmac_f32_e32 v73, v72, v72
	v_mul_f32_e32 v72, v77, v77
	v_mul_f32_e32 v74, v79, v79
	v_fmac_f32_e32 v72, v76, v76
	v_fmac_f32_e32 v74, v78, v78
	v_add_f32_e32 v72, v72, v74
	v_add_f32_e32 v72, v73, v72
	v_add_f32_e32 v72, v75, v72
	v_or_b32_e32 v92, 0x100, v92
	s_nop 0
	v_pk_fma_f32 v[66:67], s[20:21], v[66:67], v[198:199]
	s_nop 0
	v_pk_fma_f32 v[70:71], s[20:21], v[70:71], v[202:203]
	v_pk_fma_f32 v[68:69], s[4:5], v[68:69], v[200:201]
	v_pk_fma_f32 v[64:65], s[4:5], v[64:65], v[196:197]
	global_store_dwordx4 v[94:95], v[68:71], off offset:512
	global_store_dwordx4 v[94:95], v[64:67], off offset:528
	v_cvt_pk_bf16_f32 v86, v64, v65
	v_cvt_pk_bf16_f32 v87, v66, v67
	v_mul_f32_e32 v67, v67, v67
	v_mul_f32_e32 v65, v65, v65
	v_fmac_f32_e32 v67, v66, v66
	v_fmac_f32_e32 v65, v64, v64
	v_mul_f32_e32 v64, v69, v69
	v_mul_f32_e32 v66, v71, v71
	v_fmac_f32_e32 v64, v68, v68
	v_fmac_f32_e32 v66, v70, v70
	v_add_f32_e32 v64, v64, v66
	v_add_f32_e32 v64, v65, v64
	v_add_f32_e32 v64, v67, v64
	v_add_f32_e32 v64, v72, v64
	ds_bpermute_b32 v65, v116, v64
	v_cvt_pk_bf16_f32 v84, v68, v69
	v_cvt_pk_bf16_f32 v85, v70, v71
	v_lshl_add_u64 v[88:89], s[40:41], 0, v[92:93]
	global_store_dwordx4 v[88:89], v[84:87], off
	s_waitcnt lgkmcnt(0)
	v_add_f32_e32 v64, v64, v65
	ds_bpermute_b32 v65, v117, v64
	s_and_saveexec_b64 s[60:61], s[44:45]
	s_cbranch_execz .LBB0_1026
	v_lshl_add_u64 v[66:67], v[82:83], 2, s[14:15]
	s_waitcnt lgkmcnt(0)
	v_add_f32_e32 v64, v64, v65
	global_atomic_add_f32 v[66:67], v64, off
.LBB0_1026:
	s_or_b64 exec, exec, s[60:61]
	v_add_u32_e32 v64, 0x80, v142
	s_waitcnt lgkmcnt(0)
	v_ashrrev_i32_e32 v65, 31, v64
	v_lshlrev_b64 v[66:67], 10, v[64:65]
	v_lshl_add_u64 v[74:75], v[66:67], 0, v[140:141]
	v_lshlrev_b64 v[76:77], 2, v[74:75]
	v_lshl_add_u64 v[78:79], s[6:7], 0, v[76:77]
	v_lshl_add_u64 v[236:237], v[186:187], 0, v[240:241]
	global_load_dwordx4 v[188:191], v[236:237], off offset:16
	global_load_dwordx4 v[192:195], v[236:237], off
	global_load_dwordx4 v[196:199], v[236:237], off offset:528
	global_load_dwordx4 v[200:203], v[236:237], off offset:512
	s_nop 0
	v_lshlrev_b64 v[74:75], 1, v[74:75]
	v_lshl_add_u64 v[76:77], s[48:49], 0, v[76:77]
	s_waitcnt vmcnt(20)
	v_pk_fma_f32 v[58:59], s[20:21], v[58:59], v[206:207]
	s_nop 0
	v_pk_fma_f32 v[62:63], s[20:21], v[62:63], v[210:211]
	v_pk_fma_f32 v[60:61], s[4:5], v[60:61], v[208:209]
	v_pk_fma_f32 v[56:57], s[4:5], v[56:57], v[204:205]
	v_cvt_pk_bf16_f32 v66, v60, v61
	v_cvt_pk_bf16_f32 v67, v62, v63
	v_cvt_pk_bf16_f32 v68, v56, v57
	v_cvt_pk_bf16_f32 v69, v58, v59
	v_lshl_add_u64 v[70:71], s[40:41], 0, v[74:75]
	global_store_dwordx4 v[76:77], v[60:63], off
	global_store_dwordx4 v[76:77], v[56:59], off offset:16
	global_store_dwordx4 v[70:71], v[66:69], off
	s_nop 0
	s_nop 0
	s_nop 0
	v_mul_f32_e32 v59, v59, v59
	v_mul_f32_e32 v57, v57, v57
	v_fmac_f32_e32 v59, v58, v58
	v_fmac_f32_e32 v57, v56, v56
	v_mul_f32_e32 v56, v61, v61
	v_mul_f32_e32 v58, v63, v63
	v_fmac_f32_e32 v56, v60, v60
	v_fmac_f32_e32 v58, v62, v62
	v_add_f32_e32 v56, v56, v58
	v_add_f32_e32 v56, v57, v56
	v_add_f32_e32 v56, v59, v56
	v_or_b32_e32 v74, 0x100, v74
	s_nop 0
	v_pk_fma_f32 v[50:51], s[20:21], v[50:51], v[214:215]
	s_nop 0
	v_pk_fma_f32 v[54:55], s[20:21], v[54:55], v[218:219]
	v_pk_fma_f32 v[52:53], s[4:5], v[52:53], v[216:217]
	v_pk_fma_f32 v[48:49], s[4:5], v[48:49], v[212:213]
	global_store_dwordx4 v[76:77], v[52:55], off offset:512
	global_store_dwordx4 v[76:77], v[48:51], off offset:528
	v_cvt_pk_bf16_f32 v68, v48, v49
	v_cvt_pk_bf16_f32 v69, v50, v51
	v_mul_f32_e32 v51, v51, v51
	v_mul_f32_e32 v49, v49, v49
	v_fmac_f32_e32 v51, v50, v50
	v_fmac_f32_e32 v49, v48, v48
	v_mul_f32_e32 v48, v53, v53
	v_mul_f32_e32 v50, v55, v55
	v_fmac_f32_e32 v48, v52, v52
	v_fmac_f32_e32 v50, v54, v54
	v_add_f32_e32 v48, v48, v50
	v_add_f32_e32 v48, v49, v48
	v_add_f32_e32 v48, v51, v48
	v_add_f32_e32 v48, v56, v48
	ds_bpermute_b32 v49, v116, v48
	v_cvt_pk_bf16_f32 v66, v52, v53
	v_cvt_pk_bf16_f32 v67, v54, v55
	v_lshl_add_u64 v[70:71], s[40:41], 0, v[74:75]
	global_store_dwordx4 v[70:71], v[66:69], off
	s_waitcnt lgkmcnt(0)
	v_add_f32_e32 v48, v48, v49
	ds_bpermute_b32 v49, v117, v48
	s_and_saveexec_b64 s[60:61], s[44:45]
	s_cbranch_execz .LBB0_1028
	v_lshl_add_u64 v[50:51], v[64:65], 2, s[14:15]
	s_waitcnt lgkmcnt(0)
	v_add_f32_e32 v48, v48, v49
	global_atomic_add_f32 v[50:51], v48, off
.LBB0_1028:
	s_or_b64 exec, exec, s[60:61]
	v_add_u32_e32 v48, 0x90, v142
	s_waitcnt lgkmcnt(0)
	v_ashrrev_i32_e32 v49, 31, v48
	v_lshlrev_b64 v[50:51], 10, v[48:49]
	v_lshl_add_u64 v[58:59], v[50:51], 0, v[140:141]
	v_lshlrev_b64 v[60:61], 2, v[58:59]
	v_lshl_add_u64 v[62:63], s[6:7], 0, v[60:61]
	v_lshl_add_u64 v[238:239], v[236:237], 0, v[240:241]
	global_load_dwordx4 v[204:207], v[238:239], off offset:16
	global_load_dwordx4 v[208:211], v[238:239], off
	global_load_dwordx4 v[212:215], v[238:239], off offset:528
	global_load_dwordx4 v[216:219], v[238:239], off offset:512
	s_nop 0
	v_lshlrev_b64 v[58:59], 1, v[58:59]
	v_lshl_add_u64 v[60:61], s[48:49], 0, v[60:61]
	s_waitcnt vmcnt(20)
	v_pk_fma_f32 v[42:43], s[20:21], v[42:43], v[222:223]
	s_nop 0
	v_pk_fma_f32 v[46:47], s[20:21], v[46:47], v[226:227]
	v_pk_fma_f32 v[44:45], s[4:5], v[44:45], v[224:225]
	v_pk_fma_f32 v[40:41], s[4:5], v[40:41], v[220:221]
	v_cvt_pk_bf16_f32 v50, v44, v45
	v_cvt_pk_bf16_f32 v51, v46, v47
	v_cvt_pk_bf16_f32 v52, v40, v41
	v_cvt_pk_bf16_f32 v53, v42, v43
	v_lshl_add_u64 v[54:55], s[40:41], 0, v[58:59]
	global_store_dwordx4 v[60:61], v[44:47], off
	global_store_dwordx4 v[60:61], v[40:43], off offset:16
	global_store_dwordx4 v[54:55], v[50:53], off
	s_nop 0
	s_nop 0
	s_nop 0
	v_mul_f32_e32 v43, v43, v43
	v_mul_f32_e32 v41, v41, v41
	v_fmac_f32_e32 v43, v42, v42
	v_fmac_f32_e32 v41, v40, v40
	v_mul_f32_e32 v40, v45, v45
	v_mul_f32_e32 v42, v47, v47
	v_fmac_f32_e32 v40, v44, v44
	v_fmac_f32_e32 v42, v46, v46
	v_add_f32_e32 v40, v40, v42
	v_add_f32_e32 v40, v41, v40
	v_add_f32_e32 v40, v43, v40
	v_or_b32_e32 v58, 0x100, v58
	s_nop 0
	v_pk_fma_f32 v[34:35], s[20:21], v[34:35], v[230:231]
	s_nop 0
	v_pk_fma_f32 v[38:39], s[20:21], v[38:39], v[234:235]
	v_pk_fma_f32 v[36:37], s[4:5], v[36:37], v[232:233]
	v_pk_fma_f32 v[32:33], s[4:5], v[32:33], v[228:229]
	global_store_dwordx4 v[60:61], v[36:39], off offset:512
	global_store_dwordx4 v[60:61], v[32:35], off offset:528
	v_cvt_pk_bf16_f32 v52, v32, v33
	v_cvt_pk_bf16_f32 v53, v34, v35
	v_mul_f32_e32 v35, v35, v35
	v_mul_f32_e32 v33, v33, v33
	v_fmac_f32_e32 v35, v34, v34
	v_fmac_f32_e32 v33, v32, v32
	v_mul_f32_e32 v32, v37, v37
	v_mul_f32_e32 v34, v39, v39
	v_fmac_f32_e32 v32, v36, v36
	v_fmac_f32_e32 v34, v38, v38
	v_add_f32_e32 v32, v32, v34
	v_add_f32_e32 v32, v33, v32
	v_add_f32_e32 v32, v35, v32
	v_add_f32_e32 v32, v40, v32
	ds_bpermute_b32 v33, v116, v32
	v_cvt_pk_bf16_f32 v50, v36, v37
	v_cvt_pk_bf16_f32 v51, v38, v39
	v_lshl_add_u64 v[54:55], s[40:41], 0, v[58:59]
	global_store_dwordx4 v[54:55], v[50:53], off
	s_waitcnt lgkmcnt(0)
	v_add_f32_e32 v32, v32, v33
	ds_bpermute_b32 v33, v117, v32
	s_and_saveexec_b64 s[60:61], s[44:45]
	s_cbranch_execz .LBB0_1030
	v_lshl_add_u64 v[34:35], v[48:49], 2, s[14:15]
	s_waitcnt lgkmcnt(0)
	v_add_f32_e32 v32, v32, v33
	global_atomic_add_f32 v[34:35], v32, off
.LBB0_1030:
	s_or_b64 exec, exec, s[60:61]
	v_add_u32_e32 v32, 0xa0, v142
	s_waitcnt lgkmcnt(0)
	v_ashrrev_i32_e32 v33, 31, v32
	v_lshlrev_b64 v[34:35], 10, v[32:33]
	v_lshl_add_u64 v[42:43], v[34:35], 0, v[140:141]
	v_lshlrev_b64 v[44:45], 2, v[42:43]
	v_lshl_add_u64 v[46:47], s[6:7], 0, v[44:45]
	s_nop 0
	s_nop 0
	v_lshlrev_b64 v[42:43], 1, v[42:43]
	v_lshl_add_u64 v[44:45], s[48:49], 0, v[44:45]
	s_waitcnt vmcnt(16)
	v_pk_fma_f32 v[26:27], s[20:21], v[26:27], v[190:191]
	s_nop 0
	v_pk_fma_f32 v[30:31], s[20:21], v[30:31], v[194:195]
	v_pk_fma_f32 v[28:29], s[4:5], v[28:29], v[192:193]
	v_pk_fma_f32 v[24:25], s[4:5], v[24:25], v[188:189]
	v_cvt_pk_bf16_f32 v34, v28, v29
	v_cvt_pk_bf16_f32 v35, v30, v31
	v_cvt_pk_bf16_f32 v36, v24, v25
	v_cvt_pk_bf16_f32 v37, v26, v27
	v_lshl_add_u64 v[38:39], s[40:41], 0, v[42:43]
	global_store_dwordx4 v[44:45], v[28:31], off
	global_store_dwordx4 v[44:45], v[24:27], off offset:16
	global_store_dwordx4 v[38:39], v[34:37], off
	s_nop 0
	s_nop 0
	s_nop 0
	v_mul_f32_e32 v27, v27, v27
	v_mul_f32_e32 v25, v25, v25
	v_fmac_f32_e32 v27, v26, v26
	v_fmac_f32_e32 v25, v24, v24
	v_mul_f32_e32 v24, v29, v29
	v_mul_f32_e32 v26, v31, v31
	v_fmac_f32_e32 v24, v28, v28
	v_fmac_f32_e32 v26, v30, v30
	v_add_f32_e32 v24, v24, v26
	v_add_f32_e32 v24, v25, v24
	v_add_f32_e32 v24, v27, v24
	v_or_b32_e32 v42, 0x100, v42
	s_nop 0
	v_pk_fma_f32 v[18:19], s[20:21], v[18:19], v[198:199]
	s_nop 0
	v_pk_fma_f32 v[22:23], s[20:21], v[22:23], v[202:203]
	v_pk_fma_f32 v[20:21], s[4:5], v[20:21], v[200:201]
	v_pk_fma_f32 v[16:17], s[4:5], v[16:17], v[196:197]
	global_store_dwordx4 v[44:45], v[20:23], off offset:512
	global_store_dwordx4 v[44:45], v[16:19], off offset:528
	v_cvt_pk_bf16_f32 v36, v16, v17
	v_cvt_pk_bf16_f32 v37, v18, v19
	v_mul_f32_e32 v19, v19, v19
	v_mul_f32_e32 v17, v17, v17
	v_fmac_f32_e32 v19, v18, v18
	v_fmac_f32_e32 v17, v16, v16
	v_mul_f32_e32 v16, v21, v21
	v_mul_f32_e32 v18, v23, v23
	v_fmac_f32_e32 v16, v20, v20
	v_fmac_f32_e32 v18, v22, v22
	v_add_f32_e32 v16, v16, v18
	v_add_f32_e32 v16, v17, v16
	v_add_f32_e32 v16, v19, v16
	v_add_f32_e32 v16, v24, v16
	ds_bpermute_b32 v17, v116, v16
	v_cvt_pk_bf16_f32 v34, v20, v21
	v_cvt_pk_bf16_f32 v35, v22, v23
	v_lshl_add_u64 v[38:39], s[40:41], 0, v[42:43]
	global_store_dwordx4 v[38:39], v[34:37], off
	s_waitcnt lgkmcnt(0)
	v_add_f32_e32 v16, v16, v17
	ds_bpermute_b32 v17, v117, v16
	s_and_saveexec_b64 s[60:61], s[44:45]
	s_cbranch_execz .LBB0_1032
	v_lshl_add_u64 v[18:19], v[32:33], 2, s[14:15]
	s_waitcnt lgkmcnt(0)
	v_add_f32_e32 v16, v16, v17
	global_atomic_add_f32 v[18:19], v16, off
.LBB0_1032:
	s_or_b64 exec, exec, s[60:61]
	v_add_u32_e32 v16, 0xb0, v142
	s_waitcnt lgkmcnt(0)
	v_ashrrev_i32_e32 v17, 31, v16
	v_lshlrev_b64 v[18:19], 10, v[16:17]
	v_lshl_add_u64 v[26:27], v[18:19], 0, v[140:141]
	v_lshlrev_b64 v[28:29], 2, v[26:27]
	v_lshl_add_u64 v[30:31], s[6:7], 0, v[28:29]
	s_nop 0
	s_nop 0
	v_lshlrev_b64 v[26:27], 1, v[26:27]
	v_lshl_add_u64 v[28:29], s[48:49], 0, v[28:29]
	s_waitcnt vmcnt(12)
	v_pk_fma_f32 v[10:11], s[20:21], v[10:11], v[206:207]
	s_nop 0
	v_pk_fma_f32 v[14:15], s[20:21], v[14:15], v[210:211]
	v_pk_fma_f32 v[12:13], s[4:5], v[12:13], v[208:209]
	v_pk_fma_f32 v[8:9], s[4:5], v[8:9], v[204:205]
	v_cvt_pk_bf16_f32 v18, v12, v13
	v_cvt_pk_bf16_f32 v19, v14, v15
	v_cvt_pk_bf16_f32 v20, v8, v9
	v_cvt_pk_bf16_f32 v21, v10, v11
	v_lshl_add_u64 v[22:23], s[40:41], 0, v[26:27]
	global_store_dwordx4 v[28:29], v[12:15], off
	global_store_dwordx4 v[28:29], v[8:11], off offset:16
	global_store_dwordx4 v[22:23], v[18:21], off
	s_nop 0
	s_nop 0
	s_nop 0
	v_mul_f32_e32 v11, v11, v11
	v_mul_f32_e32 v9, v9, v9
	v_fmac_f32_e32 v11, v10, v10
	v_fmac_f32_e32 v9, v8, v8
	v_mul_f32_e32 v8, v13, v13
	v_mul_f32_e32 v10, v15, v15
	v_fmac_f32_e32 v8, v12, v12
	v_fmac_f32_e32 v10, v14, v14
	v_add_f32_e32 v8, v8, v10
	v_add_f32_e32 v8, v9, v8
	v_add_f32_e32 v8, v11, v8
	v_or_b32_e32 v26, 0x100, v26
	s_nop 0
	v_pk_fma_f32 v[2:3], s[20:21], v[2:3], v[214:215]
	s_nop 0
	v_pk_fma_f32 v[6:7], s[20:21], v[6:7], v[218:219]
	v_pk_fma_f32 v[4:5], s[4:5], v[4:5], v[216:217]
	v_pk_fma_f32 v[0:1], s[4:5], v[0:1], v[212:213]
	global_store_dwordx4 v[28:29], v[4:7], off offset:512
	global_store_dwordx4 v[28:29], v[0:3], off offset:528
	v_cvt_pk_bf16_f32 v20, v0, v1
	v_cvt_pk_bf16_f32 v21, v2, v3
	v_mul_f32_e32 v3, v3, v3
	v_mul_f32_e32 v1, v1, v1
	v_fmac_f32_e32 v3, v2, v2
	v_fmac_f32_e32 v1, v0, v0
	v_mul_f32_e32 v0, v5, v5
	v_mul_f32_e32 v2, v7, v7
	v_fmac_f32_e32 v0, v4, v4
	v_fmac_f32_e32 v2, v6, v6
	v_add_f32_e32 v0, v0, v2
	v_add_f32_e32 v0, v1, v0
	v_add_f32_e32 v0, v3, v0
	v_add_f32_e32 v0, v8, v0
	ds_bpermute_b32 v1, v116, v0
	v_cvt_pk_bf16_f32 v18, v4, v5
	v_cvt_pk_bf16_f32 v19, v6, v7
	v_lshl_add_u64 v[22:23], s[40:41], 0, v[26:27]
	global_store_dwordx4 v[22:23], v[18:21], off
	s_waitcnt lgkmcnt(0)
	v_add_f32_e32 v0, v0, v1
	ds_bpermute_b32 v1, v117, v0
	s_and_saveexec_b64 s[60:61], s[44:45]
	s_cbranch_execz .LBB0_1034
	v_lshl_add_u64 v[2:3], v[16:17], 2, s[14:15]
	s_waitcnt lgkmcnt(0)
	v_add_f32_e32 v0, v0, v1
	global_atomic_add_f32 v[2:3], v0, off
